# speedup vs baseline: 1.0006x; 1.0006x over previous
; #define WAIT_L(n) asm volatile("s_waitcnt lgkmcnt(" #n ")" ::: "memory")
; #define BAR __builtin_amdgcn_s_barrier()
; template <int EPI>
; __device__ __forceinline__ void phase_gemm(const Params& p, const GemmDesc& d, char* shmc) {
;     ...
;       __syncthreads();
;       {
;         const int l16 = tid2 & 15, rsub = tid2 >> 4;
; #pragma unroll
;         for (int ps = 0; ps < 8; ++ps) {
;           const int r = ps * 32 + rsub;
;           uint4 vv = *reinterpret_cast<const uint4*>(stg + r * 136 + l16 * 8);
;           *reinterpret_cast<uint4*>(d.outb + (size_t)(brow + r) * DFF + ch0 + l16 * 8) = vv;
;         }
;       }
;     }
;     WAIT_L(0);
;     BAR;
.LBB0_289:
	s_or_b64 exec, exec, s[10:11]
	s_movk_i32 s8, 0x110
	v_lshlrev_b32_e32 v162, 4, v177
	v_mul_lo_u32 v2, v175, s8
	v_add3_u32 v14, s14, v162, v2
	s_waitcnt lgkmcnt(0)
	s_barrier
	ds_read_b128 v[16:19], v14
	ds_read_b128 v[20:23], v14 offset:8704
	ds_read_b128 v[24:27], v14 offset:17408
	ds_read_b128 v[28:31], v14 offset:26112
	ds_read_b128 v[32:35], v14 offset:34816
	ds_read_b128 v[36:39], v14 offset:43520
	ds_read_b128 v[40:43], v14 offset:52224
	ds_read_b128 v[44:47], v14 offset:60928
	v_add_u32_e32 v15, s60, v175
	v_mov_b64_e32 v[10:11], s[28:29]
	v_mad_i64_i32 v[6:7], s[8:9], v15, s97, v[10:11]
	s_lshl_b64 s[8:9], s[62:63], 1
	s_nop 0
	v_lshl_add_u64 v[6:7], v[6:7], 0, s[8:9]
	v_lshl_add_u64 v[12:13], v[6:7], 0, v[162:163]
	s_waitcnt lgkmcnt(7)
	global_store_dwordx4 v[12:13], v[16:19], off
	s_add_i32 s12, s12, s15
	s_cmpk_gt_i32 s12, 0x20ff
	v_add_u32_e32 v2, 32, v15
	v_mad_i64_i32 v[2:3], s[10:11], v2, s97, v[10:11]
	v_lshl_add_u64 v[2:3], v[2:3], 0, s[8:9]
	v_lshl_add_u64 v[2:3], v[2:3], 0, v[162:163]
	s_waitcnt lgkmcnt(6)
	global_store_dwordx4 v[2:3], v[20:23], off
	s_nop 0
	v_add_u32_e32 v6, 64, v15
	v_mad_i64_i32 v[6:7], s[10:11], v6, s97, v[10:11]
	v_lshl_add_u64 v[6:7], v[6:7], 0, s[8:9]
	v_lshl_add_u64 v[12:13], v[6:7], 0, v[162:163]
	s_waitcnt lgkmcnt(5)
	global_store_dwordx4 v[12:13], v[24:27], off
	s_nop 1
	v_add_u32_e32 v2, 0x60, v15
	v_mad_i64_i32 v[2:3], s[10:11], v2, s97, v[10:11]
	v_lshl_add_u64 v[2:3], v[2:3], 0, s[8:9]
	v_lshl_add_u64 v[2:3], v[2:3], 0, v[162:163]
	s_waitcnt lgkmcnt(4)
	global_store_dwordx4 v[2:3], v[28:31], off
	s_nop 0
	v_add_u32_e32 v6, 0x80, v15
	v_mad_i64_i32 v[6:7], s[10:11], v6, s97, v[10:11]
	v_lshl_add_u64 v[6:7], v[6:7], 0, s[8:9]
	v_lshl_add_u64 v[12:13], v[6:7], 0, v[162:163]
	s_waitcnt lgkmcnt(3)
	global_store_dwordx4 v[12:13], v[32:35], off
	s_nop 1
	v_add_u32_e32 v2, 0xa0, v15
	v_mad_i64_i32 v[2:3], s[10:11], v2, s97, v[10:11]
	v_lshl_add_u64 v[2:3], v[2:3], 0, s[8:9]
	v_lshl_add_u64 v[2:3], v[2:3], 0, v[162:163]
	s_waitcnt lgkmcnt(2)
	global_store_dwordx4 v[2:3], v[36:39], off
	s_nop 0
	v_add_u32_e32 v6, 0xc0, v15
	v_mad_i64_i32 v[6:7], s[10:11], v6, s97, v[10:11]
	v_lshl_add_u64 v[6:7], v[6:7], 0, s[8:9]
	v_lshl_add_u64 v[12:13], v[6:7], 0, v[162:163]
	s_waitcnt lgkmcnt(1)
	global_store_dwordx4 v[12:13], v[40:43], off
	s_nop 1
	v_add_u32_e32 v2, 0xe0, v15
	v_mad_i64_i32 v[2:3], s[10:11], v2, s97, v[10:11]
	v_lshl_add_u64 v[2:3], v[2:3], 0, s[8:9]
	v_lshl_add_u64 v[2:3], v[2:3], 0, v[162:163]
	s_waitcnt lgkmcnt(0)
	global_store_dwordx4 v[2:3], v[44:47], off
	s_waitcnt lgkmcnt(0)
	s_cselect_b64 s[8:9], -1, 0
	s_barrier
	s_and_b64 vcc, exec, s[8:9]
	s_cbranch_vccnz .LBB0_316

; #define WAIT_L(n) asm volatile("s_waitcnt lgkmcnt(" #n ")" ::: "memory")
; #define BAR __builtin_amdgcn_s_barrier()
; template <int EPI>
; __device__ __forceinline__ void phase_gemm(const Params& p, const GemmDesc& d, char* shmc) {
;     ...
;       __syncthreads();
;       {
;         const int l16 = tid2 & 15, rsub = tid2 >> 4;
; #pragma unroll
;         for (int ps = 0; ps < 8; ++ps) {
;           const int r = ps * 32 + rsub;
;           uint4 vv = *reinterpret_cast<const uint4*>(stg + r * 136 + l16 * 8);
;           *reinterpret_cast<uint4*>(d.outb + (size_t)(brow + r) * DFF + ch0 + l16 * 8) = vv;
;         }
;       }
;     }
;     WAIT_L(0);
;     BAR;
.LBB0_1146:
	s_or_b64 exec, exec, s[10:11]
	v_lshlrev_b32_e32 v162, 4, v177
	v_mul_lo_u32 v2, v175, s87
	v_add3_u32 v14, s14, v162, v2
	s_waitcnt lgkmcnt(0)
	s_barrier
	ds_read_b128 v[16:19], v14
	ds_read_b128 v[20:23], v14 offset:8704
	ds_read_b128 v[24:27], v14 offset:17408
	ds_read_b128 v[28:31], v14 offset:26112
	ds_read_b128 v[32:35], v14 offset:34816
	ds_read_b128 v[36:39], v14 offset:43520
	ds_read_b128 v[40:43], v14 offset:52224
	ds_read_b128 v[44:47], v14 offset:60928
	v_add_u32_e32 v15, s52, v175
	v_mov_b64_e32 v[10:11], s[28:29]
	v_mad_i64_i32 v[6:7], s[8:9], v15, s88, v[10:11]
	s_lshl_b64 s[8:9], s[54:55], 1
	s_nop 0
	v_lshl_add_u64 v[6:7], v[6:7], 0, s[8:9]
	v_lshl_add_u64 v[12:13], v[6:7], 0, v[162:163]
	s_waitcnt lgkmcnt(7)
	global_store_dwordx4 v[12:13], v[16:19], off
	s_add_i32 s12, s12, s15
	s_cmpk_gt_i32 s12, 0x20ff
	v_add_u32_e32 v2, 32, v15
	v_mad_i64_i32 v[2:3], s[10:11], v2, s88, v[10:11]
	v_lshl_add_u64 v[2:3], v[2:3], 0, s[8:9]
	v_lshl_add_u64 v[2:3], v[2:3], 0, v[162:163]
	s_waitcnt lgkmcnt(6)
	global_store_dwordx4 v[2:3], v[20:23], off
	s_nop 0
	v_add_u32_e32 v6, 64, v15
	v_mad_i64_i32 v[6:7], s[10:11], v6, s88, v[10:11]
	v_lshl_add_u64 v[6:7], v[6:7], 0, s[8:9]
	v_lshl_add_u64 v[12:13], v[6:7], 0, v[162:163]
	s_waitcnt lgkmcnt(5)
	global_store_dwordx4 v[12:13], v[24:27], off
	s_nop 1
	v_add_u32_e32 v2, 0x60, v15
	v_mad_i64_i32 v[2:3], s[10:11], v2, s88, v[10:11]
	v_lshl_add_u64 v[2:3], v[2:3], 0, s[8:9]
	v_lshl_add_u64 v[2:3], v[2:3], 0, v[162:163]
	s_waitcnt lgkmcnt(4)
	global_store_dwordx4 v[2:3], v[28:31], off
	s_nop 0
	v_add_u32_e32 v6, 0x80, v15
	v_mad_i64_i32 v[6:7], s[10:11], v6, s88, v[10:11]
	v_lshl_add_u64 v[6:7], v[6:7], 0, s[8:9]
	v_lshl_add_u64 v[12:13], v[6:7], 0, v[162:163]
	s_waitcnt lgkmcnt(3)
	global_store_dwordx4 v[12:13], v[32:35], off
	s_nop 1
	v_add_u32_e32 v2, 0xa0, v15
	v_mad_i64_i32 v[2:3], s[10:11], v2, s88, v[10:11]
	v_lshl_add_u64 v[2:3], v[2:3], 0, s[8:9]
	v_lshl_add_u64 v[2:3], v[2:3], 0, v[162:163]
	s_waitcnt lgkmcnt(2)
	global_store_dwordx4 v[2:3], v[36:39], off
	s_nop 0
	v_add_u32_e32 v6, 0xc0, v15
	v_mad_i64_i32 v[6:7], s[10:11], v6, s88, v[10:11]
	v_lshl_add_u64 v[6:7], v[6:7], 0, s[8:9]
	v_lshl_add_u64 v[12:13], v[6:7], 0, v[162:163]
	s_waitcnt lgkmcnt(1)
	global_store_dwordx4 v[12:13], v[40:43], off
	s_nop 1
	v_add_u32_e32 v2, 0xe0, v15
	v_mad_i64_i32 v[2:3], s[10:11], v2, s88, v[10:11]
	v_lshl_add_u64 v[2:3], v[2:3], 0, s[8:9]
	v_lshl_add_u64 v[2:3], v[2:3], 0, v[162:163]
	s_waitcnt lgkmcnt(0)
	global_store_dwordx4 v[2:3], v[44:47], off
	s_waitcnt lgkmcnt(0)
	s_cselect_b64 s[8:9], -1, 0
	s_barrier
	s_and_b64 vcc, exec, s[8:9]
	s_cbranch_vccnz .LBB0_1173
